# layer-1 weight conversion split three ways: qkv/v/out at the head of phase 6, w13 at the head of phase 8, w2 at the head of phase 11, each by workgroups 128..255 which own one unit fewer in that phase
# speedup vs baseline: 1.0063x; 1.0006x over previous
.LBB0_21:
	s_and_b64 vcc, exec, s[0:1]
	s_cbranch_vccnz .LBB0_1371
.LBB0_22:
	s_cmp_eq_u32 s66, 1
	s_cbranch_scc0 .Lstg_n0
	s_cmp_ge_u32 s99, 192
	s_cbranch_scc0 .Lstg_end
	s_movk_i32 s98, 1200
	s_branch .Lstg_go

.Lwt1_loop:
	s_cmp_ge_u32 s16, 0x280
	s_cbranch_scc1 .Lwt1_done
	s_cmp_lt_u32 s16, 0x140
	s_cbranch_scc1 .Lwt1_d0
	s_cmp_lt_u32 s16, 0x180
	s_cbranch_scc1 .Lwt1_d1
	s_branch .Lwt1_d2

.Lwt1_d2:
	s_sub_u32 s19, s16, 0x180
	s_mov_b32 s46, 0x88
	s_mov_b32 s47, 0x0
	s_mov_b32 s48, 0x0
	s_mov_b32 s49, 0x0
	s_mov_b32 s50, 0x4500000
	s_mov_b32 s51, 0
	s_mov_b32 s26, 0x1000
	s_mov_b32 s39, 0x40000
	s_mov_b32 s27, 0x800
	s_mov_b32 s28, 0x10
	s_mov_b32 s29, 0x10000000
	s_mov_b32 s30, 0
	s_mov_b32 s31, 0x0
	s_branch .Lwt1_common
.Lwt1_common:
	s_load_dwordx2 s[20:21], s[100:101], s46
	s_cmp_lg_u32 s51, 0
	s_cbranch_scc0 .Lwt1_nog0
	s_load_dwordx2 s[22:23], s[100:101], s48

.Lwt8_skip:
	s_cmp_eq_u32 s66, 11
	s_cbranch_scc0 .Lwtb_skip
	s_cmp_ge_u32 s99, 0x80
	s_cbranch_scc0 .Lwtb_skip
	s_load_dword vcc_lo, s[100:101], 0xc0
	s_waitcnt lgkmcnt(0)
	s_cmp_eq_u32 vcc_lo, 0x100
	s_cbranch_scc0 .Lwtb_skip
	s_mov_b64 exec, -1
	v_writelane_b32 v59, s16, 0
	v_writelane_b32 v59, s17, 1
	v_writelane_b32 v59, s18, 2
	v_writelane_b32 v59, s19, 3
	v_writelane_b32 v59, s20, 4
	v_writelane_b32 v59, s21, 5
	v_writelane_b32 v59, s22, 6
	v_writelane_b32 v59, s23, 7
	v_writelane_b32 v59, s24, 8
	v_writelane_b32 v59, s25, 9
	v_writelane_b32 v59, s26, 10
	v_writelane_b32 v59, s27, 11
	v_writelane_b32 v59, s28, 12
	v_writelane_b32 v59, s29, 13
	v_writelane_b32 v59, s30, 14
	v_writelane_b32 v59, s31, 15
	v_writelane_b32 v59, s32, 16
	v_writelane_b32 v59, s33, 17
	v_writelane_b32 v59, s34, 18
	v_writelane_b32 v59, s35, 19
	v_writelane_b32 v59, s36, 20
	v_writelane_b32 v59, s37, 21
	v_writelane_b32 v59, s38, 22
	v_writelane_b32 v59, s39, 23
	v_writelane_b32 v59, s40, 24
	v_writelane_b32 v59, s41, 25
	v_writelane_b32 v59, s42, 26
	v_writelane_b32 v59, s43, 27
	v_writelane_b32 v59, s44, 28
	v_writelane_b32 v59, s45, 29
	v_writelane_b32 v59, s46, 30
	v_writelane_b32 v59, s47, 31
	v_writelane_b32 v59, s48, 32
	v_writelane_b32 v59, s49, 33
	v_writelane_b32 v59, s50, 34
	v_writelane_b32 v59, s51, 35
	v_writelane_b32 v59, s52, 36
	v_writelane_b32 v59, s53, 37
	v_writelane_b32 v59, s54, 38
	v_writelane_b32 v59, s55, 39
	s_memrealtime s[40:41]
	s_waitcnt lgkmcnt(0)
	s_add_u32 s42, s40, 1000

.Lwtb_loop:
	s_cmp_ge_u32 s16, 0x2c0
	s_cbranch_scc1 .Lwtb_done
	s_branch .Lwtb_d0
.Lwtb_d0:
	s_sub_u32 s19, s16, 0x0
	s_mov_b32 s46, 0xa0
	s_mov_b32 s47, 0xb00000
	s_mov_b32 s48, 0x0
	s_mov_b32 s49, 0x0
	s_mov_b32 s50, 0x5200000
	s_mov_b32 s51, 0
	s_mov_b32 s26, 0x1000
	s_mov_b32 s39, 0x40000
	s_mov_b32 s27, 0x1600
	s_mov_b32 s28, 0x10
	s_mov_b32 s29, 0x10000000
	s_mov_b32 s30, 0
	s_mov_b32 s31, 0x0
	s_branch .Lwtb_common
